# GEMM K-loops variant B: ds_write+load pairs spread over MFMA groups 3-4 (no tail after last MFMA), exact counted lgkm waits, K-step address prelude hoisted above barrier; in-proj row-scale (XSS) loads
# speedup vs baseline: 1.0204x; 1.0204x over previous
; DI int tid() { int t = threadIdx.x; asm volatile("" : "+v"(t)); return t; }
; #define G_LOAD(KT) do { const int k0_ = (KT) << 6; _Pragma("unroll") for (int p = 0; p < 4; ++p) { \
;     ra[p] = *(const u32x4*)(ap + (size_t)(64 * p) * lda + k0_); rb[p] = *(const u32x4*)(bp + (size_t)(64 * p) * ldb + k0_); } } while (0)
; template <bool SWAP, bool SSQ, bool ZERO = true>
; DI void gemm_main(const u16* __restrict__ A, int lda, const u16* __restrict__ Bt, int ldb, int K, char* lds,
;                   f32x16 (&acc)[4][2], float* rs_lds) {
;     ...
;   G_LOAD(0);
;   __syncthreads();
;   G_WRITE(0);
;   G_LOAD(1);
; DI void inproj_tile(const Params& p, int l, int mi, int ni, char* lds) {
;     ...
;     const int t = tid();
;     __syncthreads();
;     if (t < 256) {
;       const f32x4* ps = (const f32x4*)(p.XSS + (size_t)(m0 + t) * 32);
;       float sacc = 0.f;
; #pragma unroll
;       for (int i = 0; i < 8; ++i) { const f32x4 v = ps[i]; sacc += (v[0] + v[1]) + (v[2] + v[3]); }
;       rs[t] = rsqrtf(sacc * (1.0f / DM) + EPS);
;     }
.LBB0_87:
	s_and_b32 s52, s91, 31
	v_mov_b32_e32 v170, v222
	v_mov_b32_e32 v0, v222
	s_lshl_b32 s92, s52, 8
	s_nop 0
	v_cmp_gt_i32_e32 vcc, s60, v0
	s_barrier
	s_and_saveexec_b64 s[0:1], vcc
	s_cbranch_execz .LBB0_89
	v_add_u32_e32 v2, s92, v0
	v_ashrrev_i32_e32 v3, 31, v2
	v_lshlrev_b64 v[2:3], 7, v[2:3]
	v_lshl_add_u64 v[18:19], s[28:29], 0, v[2:3]
	global_load_dwordx4 v[64:67], v[18:19], off
	global_load_dwordx4 v[68:71], v[18:19], off offset:16
	global_load_dwordx4 v[72:75], v[18:19], off offset:32
	global_load_dwordx4 v[76:79], v[18:19], off offset:48
	global_load_dwordx4 v[80:83], v[18:19], off offset:64
	global_load_dwordx4 v[84:87], v[18:19], off offset:80
	global_load_dwordx4 v[88:91], v[18:19], off offset:96
	global_load_dwordx4 v[92:95], v[18:19], off offset:112
.LBB0_89:
	s_or_b64 exec, exec, s[0:1]
	s_and_b32 s0, s90, 0xffffff00
	s_ashr_i32 s1, s0, 31
	s_add_u32 s0, s56, s0
	s_addc_u32 s1, s57, s1
	s_and_b32 s2, s81, 31
	s_lshl_b32 s4, s2, 20
	s_lshl_b32 s2, s91, 3
	s_lshl_b64 s[0:1], s[0:1], 12
	s_and_b32 s93, s2, 0xffffff00
	s_lshl_b32 s52, s52, 20
	s_add_u32 s82, s40, s52
	s_addc_u32 s83, s41, 0
	s_ashr_i32 s53, s93, 31
	s_mul_i32 s52, s80, 0x1900
	s_add_u32 s52, s93, s52
	s_addc_u32 s53, s53, 0
	s_lshl_b64 s[52:53], s[52:53], 12
	s_add_u32 s84, s14, s52
	s_addc_u32 s85, s15, s53
	s_and_b32 s52, s91, 0xffffff80
	s_cmpk_lg_i32 s52, 0x100
	s_mov_b64 s[86:87], -1
	s_cbranch_scc0 .LBB0_116
	v_mov_b32_e32 v6, v222
	s_mov_b32 s52, 0
	v_ashrrev_i32_e32 v34, 3, v6
	v_ashrrev_i32_e32 v35, 31, v34
	v_lshlrev_b64 v[36:37], 12, v[34:35]
	v_lshlrev_b32_e32 v0, 4, v6
	v_lshl_add_u64 v[4:5], s[82:83], 0, v[36:37]
	v_and_b32_e32 v0, 0x70, v0
	v_lshl_add_u64 v[38:39], v[4:5], 0, v[0:1]
	v_lshl_add_u64 v[2:3], s[84:85], 0, v[36:37]
	v_add_co_u32_e32 v44, vcc, s54, v38
	v_lshl_add_u64 v[40:41], v[2:3], 0, v[0:1]
	s_nop 0
	v_addc_co_u32_e32 v45, vcc, 0, v39, vcc
	v_add_co_u32_e32 v46, vcc, s54, v40
	v_and_b32_e32 v7, 31, v6
	s_nop 0
	v_addc_co_u32_e32 v47, vcc, 0, v41, vcc
	v_lshrrev_b32_e32 v2, 1, v6
	v_add_co_u32_e32 v48, vcc, s55, v38
	v_and_or_b32 v35, v2, s7, v7
	v_and_b32_e32 v42, 16, v2
	v_and_b32_e32 v43, 0xdf, v6
	global_load_dwordx4 v[2:5], v[38:39], off
	global_load_dwordx4 v[6:9], v[40:41], off
	v_addc_co_u32_e32 v49, vcc, 0, v39, vcc
	v_add_co_u32_e32 v50, vcc, s55, v40
	global_load_dwordx4 v[10:13], v[44:45], off
	s_nop 0
	v_addc_co_u32_e32 v51, vcc, 0, v41, vcc
	global_load_dwordx4 v[14:17], v[46:47], off
	v_add_co_u32_e32 v52, vcc, s8, v38
	global_load_dwordx4 v[18:21], v[48:49], off
	s_nop 0
	v_addc_co_u32_e32 v53, vcc, 0, v39, vcc
	global_load_dwordx4 v[22:25], v[50:51], off
	v_add_co_u32_e32 v54, vcc, s8, v40
	global_load_dwordx4 v[26:29], v[52:53], off
	s_nop 0
	v_addc_co_u32_e32 v55, vcc, 0, v41, vcc
	global_load_dwordx4 v[30:33], v[54:55], off
	v_mad_u64_u32 v[162:163], s[62:63], v34, s9, v[0:1]
	v_cmp_gt_i32_e32 vcc, s60, v222
	s_and_saveexec_b64 s[100:101], vcc
	s_cbranch_execz .Lxss_done_a
	s_waitcnt vmcnt(8)
	v_pk_add_f32 v[64:65], v[64:65], v[66:67]
	v_pk_add_f32 v[68:69], v[68:69], v[70:71]
	v_pk_add_f32 v[72:73], v[72:73], v[74:75]
	v_pk_add_f32 v[76:77], v[76:77], v[78:79]
	v_pk_add_f32 v[80:81], v[80:81], v[82:83]
	v_pk_add_f32 v[84:85], v[84:85], v[86:87]
	v_pk_add_f32 v[88:89], v[88:89], v[90:91]
	v_pk_add_f32 v[92:93], v[92:93], v[94:95]
	v_pk_add_f32 v[64:65], v[64:65], v[68:69]
	v_pk_add_f32 v[72:73], v[72:73], v[76:77]
	v_pk_add_f32 v[80:81], v[80:81], v[84:85]
	v_pk_add_f32 v[88:89], v[88:89], v[92:93]
	v_pk_add_f32 v[64:65], v[64:65], v[72:73]
	v_pk_add_f32 v[80:81], v[80:81], v[88:89]
	v_pk_add_f32 v[64:65], v[64:65], v[80:81]
	v_add_f32_e32 v64, v64, v65
	v_fmamk_f32 v64, v64, 0x3a000000, v223
	v_cmp_gt_f32_e32 vcc, s58, v64
	v_mul_f32_e32 v65, 0x4b800000, v64
	s_nop 0
	v_cndmask_b32_e32 v64, v64, v65, vcc
	v_rsq_f32_e32 v64, v64
	s_nop 0
	v_mul_f32_e32 v65, 0x45800000, v64
	v_cndmask_b32_e32 v64, v64, v65, vcc
	v_lshl_add_u32 v66, v222, 2, v227
	ds_write_b32 v66, v64
.Lxss_done_a:
	s_or_b64 exec, exec, s[100:101]
	s_waitcnt lgkmcnt(0)
	s_barrier
	v_mad_u64_u32 v[164:165], s[62:63], v35, s9, v[42:43]
	v_mad_u32_u24 v163, v43, s9, v42
	s_mov_b64 s[86:87], 0
	s_mov_b32 s53, 2
	s_waitcnt vmcnt(7)
	ds_write_b128 v162, v[2:5]
	s_waitcnt vmcnt(6)
	ds_write_b128 v162, v[6:9] offset:36864
	s_waitcnt vmcnt(5)
	ds_write_b128 v162, v[10:13] offset:9216
	s_waitcnt vmcnt(4)
	ds_write_b128 v162, v[14:17] offset:46080
	s_waitcnt vmcnt(3)
	ds_write_b128 v162, v[18:21] offset:18432
	s_waitcnt vmcnt(2)
	ds_write_b128 v162, v[22:25] offset:55296
	s_waitcnt vmcnt(1)
	ds_write_b128 v162, v[26:29] offset:27648
	s_waitcnt vmcnt(0)
; #define G_LOAD(KT) do { const int k0_ = (KT) << 6; _Pragma("unroll") for (int p = 0; p < 4; ++p) { \
;     ra[p] = *(const u32x4*)(ap + (size_t)(64 * p) * lda + k0_); rb[p] = *(const u32x4*)(bp + (size_t)(64 * p) * ldb + k0_); } } while (0)
; template <bool SWAP, bool SSQ, bool ZERO = true>
; DI void gemm_main(const u16* __restrict__ A, int lda, const u16* __restrict__ Bt, int ldb, int K, char* lds,
;                   f32x16 (&acc)[4][2], float* rs_lds) {
;     ...
;   G_LOAD(0);
;   __syncthreads();
;   G_WRITE(0);
;   G_LOAD(1);
;   __syncthreads();
; #pragma nounroll
;   for (int kt = 0; kt < nk; ++kt) {
;     const int st = (kt & 1) * 2 * G_TILE;
;     ...
;     if (kt + 1 < nk) G_WRITE((kt + 1) & 1);
;     if (kt + 2 < nk) G_LOAD(kt + 2);
;     __syncthreads();
	ds_write_b128 v162, v[30:33] offset:64512
	global_load_dwordx4 v[130:133], v[38:39], off offset:128
	global_load_dwordx4 v[134:137], v[40:41], off offset:128
	global_load_dwordx4 v[138:141], v[44:45], off offset:128
	global_load_dwordx4 v[142:145], v[46:47], off offset:128
	global_load_dwordx4 v[146:149], v[48:49], off offset:128
	global_load_dwordx4 v[150:153], v[50:51], off offset:128
	global_load_dwordx4 v[154:157], v[52:53], off offset:128
	global_load_dwordx4 v[158:161], v[54:55], off offset:128
	v_lshl_add_u64 v[2:3], s[0:1], 0, v[36:37]
	v_lshl_add_u64 v[2:3], v[2:3], 0, v[0:1]
	v_lshl_add_u64 v[166:167], s[14:15], 0, v[2:3]
	v_lshl_add_u64 v[2:3], s[4:5], 0, v[36:37]
	v_lshl_add_u64 v[2:3], v[2:3], 0, v[0:1]
	v_lshl_add_u64 v[168:169], s[40:41], 0, v[2:3]
	v_mov_b32_e32 v2, 0
	v_mov_b32_e32 v3, v2
	v_mov_b32_e32 v4, v2
	v_mov_b32_e32 v5, v2
	v_mov_b32_e32 v6, v2
	v_mov_b32_e32 v7, v2
	v_mov_b32_e32 v8, v2
	v_mov_b32_e32 v9, v2
	v_mov_b32_e32 v10, v2
	v_mov_b32_e32 v11, v2
	v_mov_b32_e32 v12, v2
	v_mov_b32_e32 v13, v2
	v_mov_b32_e32 v14, v2
	v_mov_b32_e32 v15, v2
	v_mov_b32_e32 v16, v2
	v_mov_b32_e32 v17, v2
	v_mov_b32_e32 v18, v2
	v_mov_b32_e32 v19, v2
	v_mov_b32_e32 v20, v2
	v_mov_b32_e32 v21, v2
	v_mov_b32_e32 v22, v2
	v_mov_b32_e32 v23, v2
	v_mov_b32_e32 v24, v2
	v_mov_b32_e32 v25, v2
	v_mov_b32_e32 v26, v2
	v_mov_b32_e32 v27, v2
	v_mov_b32_e32 v28, v2
	v_mov_b32_e32 v29, v2
	v_mov_b32_e32 v30, v2
	v_mov_b32_e32 v31, v2
	v_mov_b32_e32 v32, v2
	v_mov_b32_e32 v33, v2
	v_mov_b32_e32 v34, v2
	v_mov_b32_e32 v35, v2
	v_mov_b32_e32 v36, v2
	v_mov_b32_e32 v37, v2
	v_mov_b32_e32 v38, v2
	v_mov_b32_e32 v39, v2
	v_mov_b32_e32 v40, v2
	v_mov_b32_e32 v41, v2
	v_mov_b32_e32 v42, v2
	v_mov_b32_e32 v43, v2
	v_mov_b32_e32 v44, v2
	v_mov_b32_e32 v45, v2
	v_mov_b32_e32 v46, v2
	v_mov_b32_e32 v47, v2
	v_mov_b32_e32 v48, v2
	v_mov_b32_e32 v49, v2
	v_mov_b32_e32 v50, v2
	v_mov_b32_e32 v51, v2
	v_mov_b32_e32 v52, v2
	v_mov_b32_e32 v53, v2
	v_mov_b32_e32 v54, v2
	v_mov_b32_e32 v55, v2
	v_mov_b32_e32 v56, v2
	v_mov_b32_e32 v57, v2
	v_mov_b32_e32 v58, v2
	v_mov_b32_e32 v59, v2
	v_mov_b32_e32 v60, v2
	v_mov_b32_e32 v61, v2
	v_mov_b32_e32 v62, v2
	v_mov_b32_e32 v63, v2
	v_mov_b32_e32 v64, v2
	v_mov_b32_e32 v65, v2
	v_mov_b32_e32 v66, v2
	v_mov_b32_e32 v67, v2
	v_mov_b32_e32 v68, v2
	v_mov_b32_e32 v69, v2
	v_mov_b32_e32 v70, v2
	v_mov_b32_e32 v71, v2
	v_mov_b32_e32 v72, v2
	v_mov_b32_e32 v73, v2
	v_mov_b32_e32 v74, v2
	v_mov_b32_e32 v75, v2
	v_mov_b32_e32 v76, v2
	v_mov_b32_e32 v77, v2
	v_mov_b32_e32 v78, v2
	v_mov_b32_e32 v79, v2
	v_mov_b32_e32 v80, v2
	v_mov_b32_e32 v81, v2
	v_mov_b32_e32 v82, v2
	v_mov_b32_e32 v83, v2
	v_mov_b32_e32 v84, v2
	v_mov_b32_e32 v85, v2
	v_mov_b32_e32 v86, v2
	v_mov_b32_e32 v87, v2
	v_mov_b32_e32 v88, v2
	v_mov_b32_e32 v89, v2
	v_mov_b32_e32 v90, v2
	v_mov_b32_e32 v91, v2
	v_mov_b32_e32 v92, v2
	v_mov_b32_e32 v93, v2
	v_mov_b32_e32 v94, v2
	v_mov_b32_e32 v95, v2
	v_mov_b32_e32 v96, v2
	v_mov_b32_e32 v97, v2
	v_mov_b32_e32 v98, v2
	v_mov_b32_e32 v99, v2
	v_mov_b32_e32 v100, v2
	v_mov_b32_e32 v101, v2
	v_mov_b32_e32 v102, v2
	v_mov_b32_e32 v103, v2
	v_mov_b32_e32 v104, v2
	v_mov_b32_e32 v105, v2
	v_mov_b32_e32 v106, v2
	v_mov_b32_e32 v107, v2
	v_mov_b32_e32 v108, v2
	v_mov_b32_e32 v109, v2
	v_mov_b32_e32 v110, v2
	v_mov_b32_e32 v111, v2
	v_mov_b32_e32 v112, v2
	v_mov_b32_e32 v113, v2
	v_mov_b32_e32 v114, v2
	v_mov_b32_e32 v115, v2
	v_mov_b32_e32 v116, v2
	v_mov_b32_e32 v117, v2
	v_mov_b32_e32 v118, v2
	v_mov_b32_e32 v119, v2
	v_mov_b32_e32 v120, v2
	v_mov_b32_e32 v121, v2
	v_mov_b32_e32 v122, v2
	v_mov_b32_e32 v123, v2
	v_mov_b32_e32 v124, v2
	v_mov_b32_e32 v125, v2
	v_mov_b32_e32 v126, v2
	v_mov_b32_e32 v127, v2
	v_mov_b32_e32 v128, v2
	v_mov_b32_e32 v129, v2
	s_add_i32 s62, s53, -2
	s_and_b32 s62, s62, 2
	s_mul_i32 s62, s62, 0x9000
	v_add_u32_e32 v0, s62, v164
	v_add_u32_e32 v165, s62, v163
	s_waitcnt lgkmcnt(0)
	s_barrier
	s_branch .LBB0_92
.LBB0_91:
	s_add_u32 s86, s86, 0x80
	s_addc_u32 s87, s87, 0
	s_add_i32 s53, s53, 2
	s_add_i32 s52, s52, 1
	s_add_i32 s62, s53, -2
	s_and_b32 s62, s62, 2
	s_mul_i32 s62, s62, 0x9000
	v_add_u32_e32 v0, s62, v164
	v_add_u32_e32 v165, s62, v163
	s_cmpk_lg_i32 s86, 0x1000
	s_waitcnt lgkmcnt(0)
	s_barrier
	s_cbranch_scc0 .LBB0_96
; #define MFMA32(a, b, c) __builtin_amdgcn_mfma_f32_32x32x16_bf16((a), (b), (c), 0, 0, 0)
; #define G_LOAD(KT) do { const int k0_ = (KT) << 6; _Pragma("unroll") for (int p = 0; p < 4; ++p) { \
;     ra[p] = *(const u32x4*)(ap + (size_t)(64 * p) * lda + k0_); rb[p] = *(const u32x4*)(bp + (size_t)(64 * p) * ldb + k0_); } } while (0)
; template <bool SWAP, bool SSQ, bool ZERO = true>
; DI void gemm_main(const u16* __restrict__ A, int lda, const u16* __restrict__ Bt, int ldb, int K, char* lds,
;                   f32x16 (&acc)[4][2], float* rs_lds) {
;     ...
;   for (int kt = 0; kt < nk; ++kt) {
;     const int st = (kt & 1) * 2 * G_TILE;
;     {
;       bf16x8 fa[2][4], fb[2][2];
; #pragma unroll
;       for (int i = 0; i < 4; ++i) fa[0][i] = *(const bf16x8*)(abase + st + i * 32 * GS);
; #pragma unroll
;       for (int i = 0; i < 2; ++i) fb[0][i] = *(const bf16x8*)(bbase + st + i * 32 * GS);
; #pragma unroll
;       for (int ks = 0; ks < 4; ++ks) {
;         if (ks + 1 < 4) {
; #pragma unroll
;           for (int i = 0; i < 4; ++i) fa[(ks + 1) & 1][i] = *(const bf16x8*)(abase + st + i * 32 * GS + (ks + 1) * 32);
; #pragma unroll
;           for (int i = 0; i < 2; ++i) fb[(ks + 1) & 1][i] = *(const bf16x8*)(bbase + st + i * 32 * GS + (ks + 1) * 32);
;         }
;         __builtin_amdgcn_sched_barrier(0);
;         __builtin_amdgcn_s_setprio(1);
; #pragma unroll
;         for (int mt = 0; mt < 4; ++mt)
; #pragma unroll
;           for (int nt = 0; nt < 2; ++nt)
;             acc[mt][nt] = SWAP ? MFMA32(fb[ks & 1][nt], fa[ks & 1][mt], acc[mt][nt]) : MFMA32(fa[ks & 1][mt], fb[ks & 1][nt], acc[mt][nt]);
;         __builtin_amdgcn_s_setprio(0);
;         __builtin_amdgcn_sched_barrier(0);
;       }
;     }
;     if (kt + 1 < nk) G_WRITE((kt + 1) & 1);
;     if (kt + 2 < nk) G_LOAD(kt + 2);
;     __syncthreads();
;   }
.LBB0_92:
	ds_read_b128 v[204:207], v165 offset:36864
	ds_read_b128 v[172:175], v0
	ds_read_b128 v[212:215], v165 offset:41472
	ds_read_b128 v[180:183], v0 offset:4608
	ds_read_b128 v[188:191], v0 offset:9216
	ds_read_b128 v[196:199], v0 offset:13824
	ds_read_b128 v[208:211], v165 offset:36896
	ds_read_b128 v[176:179], v0 offset:32
	ds_read_b128 v[216:219], v165 offset:41504
	ds_read_b128 v[184:187], v0 offset:4640
	ds_read_b128 v[192:195], v0 offset:9248
	ds_read_b128 v[200:203], v0 offset:13856
	s_setprio 1
	s_waitcnt lgkmcnt(10)
	v_mfma_f32_32x32x16_bf16 v[114:129], v[204:207], v[172:175], v[114:129]
	s_waitcnt lgkmcnt(9)
	v_mfma_f32_32x32x16_bf16 v[98:113], v[212:215], v[172:175], v[98:113]
	s_waitcnt lgkmcnt(8)
	v_mfma_f32_32x32x16_bf16 v[82:97], v[204:207], v[180:183], v[82:97]
	v_mfma_f32_32x32x16_bf16 v[66:81], v[212:215], v[180:183], v[66:81]
	s_waitcnt lgkmcnt(7)
	v_mfma_f32_32x32x16_bf16 v[50:65], v[204:207], v[188:191], v[50:65]
	v_mfma_f32_32x32x16_bf16 v[34:49], v[212:215], v[188:191], v[34:49]
	s_waitcnt lgkmcnt(6)
	v_mfma_f32_32x32x16_bf16 v[18:33], v[204:207], v[196:199], v[18:33]
	v_mfma_f32_32x32x16_bf16 v[2:17], v[212:215], v[196:199], v[2:17]
	s_setprio 0
	ds_read_b128 v[204:207], v165 offset:36928
	ds_read_b128 v[172:175], v0 offset:64
	ds_read_b128 v[212:215], v165 offset:41536
	ds_read_b128 v[180:183], v0 offset:4672
	ds_read_b128 v[188:191], v0 offset:9280
	ds_read_b128 v[196:199], v0 offset:13888
	s_setprio 1
	s_waitcnt lgkmcnt(10)
	v_mfma_f32_32x32x16_bf16 v[114:129], v[208:211], v[176:179], v[114:129]
	s_waitcnt lgkmcnt(9)
	v_mfma_f32_32x32x16_bf16 v[98:113], v[216:219], v[176:179], v[98:113]
	s_waitcnt lgkmcnt(8)
	v_mfma_f32_32x32x16_bf16 v[82:97], v[208:211], v[184:187], v[82:97]
	v_mfma_f32_32x32x16_bf16 v[66:81], v[216:219], v[184:187], v[66:81]
	s_waitcnt lgkmcnt(7)
	v_mfma_f32_32x32x16_bf16 v[50:65], v[208:211], v[192:195], v[50:65]
	v_mfma_f32_32x32x16_bf16 v[34:49], v[216:219], v[192:195], v[34:49]
	s_waitcnt lgkmcnt(6)
	v_mfma_f32_32x32x16_bf16 v[18:33], v[208:211], v[200:203], v[18:33]
	v_mfma_f32_32x32x16_bf16 v[2:17], v[216:219], v[200:203], v[2:17]
	s_setprio 0
	ds_read_b128 v[208:211], v165 offset:36960
	ds_read_b128 v[176:179], v0 offset:96
	ds_read_b128 v[216:219], v165 offset:41568
	ds_read_b128 v[184:187], v0 offset:4704
	ds_read_b128 v[192:195], v0 offset:9312
	ds_read_b128 v[200:203], v0 offset:13920
	s_cmp_gt_u32 s52, 29
	s_cbranch_scc1 .Lg92_tail
	s_setprio 1
	s_waitcnt lgkmcnt(10)
	v_mfma_f32_32x32x16_bf16 v[114:129], v[204:207], v[172:175], v[114:129]
	s_waitcnt lgkmcnt(9)
	v_mfma_f32_32x32x16_bf16 v[98:113], v[212:215], v[172:175], v[98:113]
	s_waitcnt lgkmcnt(8)
	v_mfma_f32_32x32x16_bf16 v[82:97], v[204:207], v[180:183], v[82:97]
	v_mfma_f32_32x32x16_bf16 v[66:81], v[212:215], v[180:183], v[66:81]
	s_and_b32 s62, s53, 2
	s_mul_i32 s62, s62, 0x9000
	v_add_u32_e32 v240, s62, v162
	v_lshl_add_u64 v[220:221], v[168:169], 0, s[86:87]
	v_lshl_add_u64 v[234:235], v[166:167], 0, s[86:87]
	s_waitcnt lgkmcnt(7)
	v_mfma_f32_32x32x16_bf16 v[50:65], v[204:207], v[188:191], v[50:65]
	s_waitcnt vmcnt(7)
	ds_write_b128 v240, v[130:133]
	global_load_dwordx4 v[130:133], v[220:221], off offset:256
	v_add_co_u32_e32 v220, vcc, 0x40000, v220
	v_mfma_f32_32x32x16_bf16 v[34:49], v[212:215], v[188:191], v[34:49]
	s_waitcnt vmcnt(7)
	ds_write_b128 v240, v[134:137] offset:36864
	v_addc_co_u32_e32 v221, vcc, 0, v221, vcc
	global_load_dwordx4 v[134:137], v[234:235], off offset:256
	v_add_co_u32_e32 v234, vcc, 0x40000, v234
	s_waitcnt lgkmcnt(8)
	v_mfma_f32_32x32x16_bf16 v[18:33], v[204:207], v[196:199], v[18:33]
	s_waitcnt vmcnt(7)
	ds_write_b128 v240, v[138:141] offset:9216
	v_addc_co_u32_e32 v235, vcc, 0, v235, vcc
	global_load_dwordx4 v[138:141], v[220:221], off offset:256
	v_add_co_u32_e32 v220, vcc, 0x40000, v220
	v_mfma_f32_32x32x16_bf16 v[2:17], v[212:215], v[196:199], v[2:17]
	s_waitcnt vmcnt(7)
	ds_write_b128 v240, v[142:145] offset:46080
	v_addc_co_u32_e32 v221, vcc, 0, v221, vcc
	global_load_dwordx4 v[142:145], v[234:235], off offset:256
	v_add_co_u32_e32 v234, vcc, 0x40000, v234
	s_waitcnt lgkmcnt(8)
	v_mfma_f32_32x32x16_bf16 v[114:129], v[208:211], v[176:179], v[114:129]
	s_waitcnt vmcnt(7)
	ds_write_b128 v240, v[146:149] offset:18432
	v_addc_co_u32_e32 v235, vcc, 0, v235, vcc
	global_load_dwordx4 v[146:149], v[220:221], off offset:256
	v_add_co_u32_e32 v220, vcc, 0x40000, v220
	s_waitcnt lgkmcnt(8)
	v_mfma_f32_32x32x16_bf16 v[98:113], v[216:219], v[176:179], v[98:113]
	s_waitcnt vmcnt(7)
	ds_write_b128 v240, v[150:153] offset:55296
	v_addc_co_u32_e32 v221, vcc, 0, v221, vcc
	global_load_dwordx4 v[150:153], v[234:235], off offset:256
	v_add_co_u32_e32 v234, vcc, 0x40000, v234
	s_waitcnt lgkmcnt(8)
	v_mfma_f32_32x32x16_bf16 v[82:97], v[208:211], v[184:187], v[82:97]
	s_waitcnt vmcnt(7)
	ds_write_b128 v240, v[154:157] offset:27648
	v_addc_co_u32_e32 v235, vcc, 0, v235, vcc
	global_load_dwordx4 v[154:157], v[220:221], off offset:256
	v_mfma_f32_32x32x16_bf16 v[66:81], v[216:219], v[184:187], v[66:81]
	s_waitcnt vmcnt(7)
	ds_write_b128 v240, v[158:161] offset:64512
	global_load_dwordx4 v[158:161], v[234:235], off offset:256
	s_waitcnt lgkmcnt(9)
	v_mfma_f32_32x32x16_bf16 v[50:65], v[208:211], v[192:195], v[50:65]
	v_mfma_f32_32x32x16_bf16 v[34:49], v[216:219], v[192:195], v[34:49]
	s_waitcnt lgkmcnt(8)
	v_mfma_f32_32x32x16_bf16 v[18:33], v[208:211], v[200:203], v[18:33]
	v_mfma_f32_32x32x16_bf16 v[2:17], v[216:219], v[200:203], v[2:17]
	s_setprio 0
	s_branch .LBB0_91
; #define MFMA32(a, b, c) __builtin_amdgcn_mfma_f32_32x32x16_bf16((a), (b), (c), 0, 0, 0)
; #define G_LOAD(KT) do { const int k0_ = (KT) << 6; _Pragma("unroll") for (int p = 0; p < 4; ++p) { \
;     ra[p] = *(const u32x4*)(ap + (size_t)(64 * p) * lda + k0_); rb[p] = *(const u32x4*)(bp + (size_t)(64 * p) * ldb + k0_); } } while (0)
; template <bool SWAP, bool SSQ, bool ZERO = true>
; DI void gemm_main(const u16* __restrict__ A, int lda, const u16* __restrict__ Bt, int ldb, int K, char* lds,
;                   f32x16 (&acc)[4][2], float* rs_lds) {
;     ...
;       for (int ks = 0; ks < 4; ++ks) {
;         if (ks + 1 < 4) {
; #pragma unroll
;           for (int i = 0; i < 4; ++i) fa[(ks + 1) & 1][i] = *(const bf16x8*)(abase + st + i * 32 * GS + (ks + 1) * 32);
; #pragma unroll
;           for (int i = 0; i < 2; ++i) fb[(ks + 1) & 1][i] = *(const bf16x8*)(bbase + st + i * 32 * GS + (ks + 1) * 32);
;         }
;         __builtin_amdgcn_sched_barrier(0);
;         __builtin_amdgcn_s_setprio(1);
; #pragma unroll
;         for (int mt = 0; mt < 4; ++mt)
; #pragma unroll
;           for (int nt = 0; nt < 2; ++nt)
;             acc[mt][nt] = SWAP ? MFMA32(fb[ks & 1][nt], fa[ks & 1][mt], acc[mt][nt]) : MFMA32(fa[ks & 1][mt], fb[ks & 1][nt], acc[mt][nt]);
;         __builtin_amdgcn_s_setprio(0);
;         __builtin_amdgcn_sched_barrier(0);
;       }
;     }
;     if (kt + 1 < nk) G_WRITE((kt + 1) & 1);
;     if (kt + 2 < nk) G_LOAD(kt + 2);
;     __syncthreads();
.Lg92_tail:
	s_setprio 1
	s_waitcnt lgkmcnt(10)
	v_mfma_f32_32x32x16_bf16 v[114:129], v[204:207], v[172:175], v[114:129]
	s_waitcnt lgkmcnt(9)
	v_mfma_f32_32x32x16_bf16 v[98:113], v[212:215], v[172:175], v[98:113]
	s_waitcnt lgkmcnt(8)
	v_mfma_f32_32x32x16_bf16 v[82:97], v[204:207], v[180:183], v[82:97]
	v_mfma_f32_32x32x16_bf16 v[66:81], v[212:215], v[180:183], v[66:81]
	s_waitcnt lgkmcnt(7)
	v_mfma_f32_32x32x16_bf16 v[50:65], v[204:207], v[188:191], v[50:65]
	v_mfma_f32_32x32x16_bf16 v[34:49], v[212:215], v[188:191], v[34:49]
	s_waitcnt lgkmcnt(6)
	v_mfma_f32_32x32x16_bf16 v[18:33], v[204:207], v[196:199], v[18:33]
	v_mfma_f32_32x32x16_bf16 v[2:17], v[212:215], v[196:199], v[2:17]
	s_waitcnt lgkmcnt(4)
	v_mfma_f32_32x32x16_bf16 v[114:129], v[208:211], v[176:179], v[114:129]
	s_waitcnt lgkmcnt(3)
	v_mfma_f32_32x32x16_bf16 v[98:113], v[216:219], v[176:179], v[98:113]
	s_waitcnt lgkmcnt(2)
	v_mfma_f32_32x32x16_bf16 v[82:97], v[208:211], v[184:187], v[82:97]
	v_mfma_f32_32x32x16_bf16 v[66:81], v[216:219], v[184:187], v[66:81]
	s_waitcnt lgkmcnt(1)
	v_mfma_f32_32x32x16_bf16 v[50:65], v[208:211], v[192:195], v[50:65]
	v_mfma_f32_32x32x16_bf16 v[34:49], v[216:219], v[192:195], v[34:49]
	s_waitcnt lgkmcnt(0)
	v_mfma_f32_32x32x16_bf16 v[18:33], v[208:211], v[200:203], v[18:33]
	v_mfma_f32_32x32x16_bf16 v[2:17], v[216:219], v[200:203], v[2:17]
	s_setprio 0
	s_cmpk_eq_i32 s86, 0xf80
	s_cbranch_scc1 .LBB0_94
	s_and_b32 s62, s53, 2
	s_mul_i32 s62, s62, 0x9000
	v_add_u32_e32 v0, s62, v162
	s_waitcnt vmcnt(7)
	ds_write_b128 v0, v[130:133]
	s_waitcnt vmcnt(6)
	ds_write_b128 v0, v[134:137] offset:36864
	s_waitcnt vmcnt(5)
	ds_write_b128 v0, v[138:141] offset:9216
	s_waitcnt vmcnt(4)
	ds_write_b128 v0, v[142:145] offset:46080
	s_waitcnt vmcnt(3)
	ds_write_b128 v0, v[146:149] offset:18432
	s_waitcnt vmcnt(2)
	ds_write_b128 v0, v[150:153] offset:55296
	s_waitcnt vmcnt(1)
	ds_write_b128 v0, v[154:157] offset:27648
	s_waitcnt vmcnt(0)
	ds_write_b128 v0, v[158:161] offset:64512

; DI int tid() { int t = threadIdx.x; asm volatile("" : "+v"(t)); return t; }
; #define G_LOAD(KT) do { const int k0_ = (KT) << 6; _Pragma("unroll") for (int p = 0; p < 4; ++p) { \
;     ra[p] = *(const u32x4*)(ap + (size_t)(64 * p) * lda + k0_); rb[p] = *(const u32x4*)(bp + (size_t)(64 * p) * ldb + k0_); } } while (0)
; template <bool SWAP, bool SSQ, bool ZERO = true>
; DI void gemm_main(const u16* __restrict__ A, int lda, const u16* __restrict__ Bt, int ldb, int K, char* lds,
;                   f32x16 (&acc)[4][2], float* rs_lds) {
;     ...
;   G_LOAD(0);
;   __syncthreads();
;   G_WRITE(0);
;   G_LOAD(1);
;   __syncthreads();
; DI void inproj_tile(const Params& p, int l, int mi, int ni, char* lds) {
;     ...
;     const int t = tid();
;     __syncthreads();
;     if (t < 256) {
;       const f32x4* ps = (const f32x4*)(p.XSS + (size_t)(m0 + t) * 32);
;       float sacc = 0.f;
; #pragma unroll
;       for (int i = 0; i < 8; ++i) { const f32x4 v = ps[i]; sacc += (v[0] + v[1]) + (v[2] + v[3]); }
;       rs[t] = rsqrtf(sacc * (1.0f / DM) + EPS);
;     }
;   }
;   if (n0 >= 2048 && n0 < 3072) {
;     gemm_main<false, false>(A, DM, Bt, DM, DM, lds, acc, rs);
.LBB0_116:
	s_and_b64 vcc, exec, s[86:87]
	s_cbranch_vccz .LBB0_86
	v_mov_b32_e32 v6, v222
	s_mov_b32 s2, 0
	v_ashrrev_i32_e32 v34, 3, v6
	v_ashrrev_i32_e32 v35, 31, v34
	v_lshlrev_b64 v[36:37], 12, v[34:35]
	v_lshlrev_b32_e32 v0, 4, v6
	v_lshl_add_u64 v[4:5], s[82:83], 0, v[36:37]
	v_and_b32_e32 v0, 0x70, v0
	v_lshl_add_u64 v[38:39], v[4:5], 0, v[0:1]
	v_lshl_add_u64 v[2:3], s[84:85], 0, v[36:37]
	v_add_co_u32_e32 v44, vcc, s54, v38
	v_lshl_add_u64 v[40:41], v[2:3], 0, v[0:1]
	s_nop 0
	v_addc_co_u32_e32 v45, vcc, 0, v39, vcc
	v_add_co_u32_e32 v46, vcc, s54, v40
	v_and_b32_e32 v7, 31, v6
	s_nop 0
	v_addc_co_u32_e32 v47, vcc, 0, v41, vcc
	v_lshrrev_b32_e32 v2, 1, v6
	v_add_co_u32_e32 v48, vcc, s55, v38
	v_and_or_b32 v35, v2, s7, v7
	v_and_b32_e32 v42, 16, v2
	v_and_b32_e32 v43, 0xdf, v6
	global_load_dwordx4 v[2:5], v[38:39], off
	global_load_dwordx4 v[6:9], v[40:41], off
	v_addc_co_u32_e32 v49, vcc, 0, v39, vcc
	v_add_co_u32_e32 v50, vcc, s55, v40
	global_load_dwordx4 v[10:13], v[44:45], off
	s_nop 0
	v_addc_co_u32_e32 v51, vcc, 0, v41, vcc
	global_load_dwordx4 v[14:17], v[46:47], off
	v_add_co_u32_e32 v52, vcc, s8, v38
	global_load_dwordx4 v[18:21], v[48:49], off
	s_nop 0
	v_addc_co_u32_e32 v53, vcc, 0, v39, vcc
	global_load_dwordx4 v[22:25], v[50:51], off
	v_add_co_u32_e32 v54, vcc, s8, v40
	global_load_dwordx4 v[26:29], v[52:53], off
	s_nop 0
	v_addc_co_u32_e32 v55, vcc, 0, v41, vcc
	global_load_dwordx4 v[30:33], v[54:55], off
	v_mad_u64_u32 v[162:163], s[52:53], v34, s9, v[0:1]
	v_cmp_gt_i32_e32 vcc, s60, v222
	s_and_saveexec_b64 s[100:101], vcc
	s_cbranch_execz .Lxss_done_b
	s_waitcnt vmcnt(8)
	v_pk_add_f32 v[64:65], v[64:65], v[66:67]
	v_pk_add_f32 v[68:69], v[68:69], v[70:71]
	v_pk_add_f32 v[72:73], v[72:73], v[74:75]
	v_pk_add_f32 v[76:77], v[76:77], v[78:79]
	v_pk_add_f32 v[80:81], v[80:81], v[82:83]
	v_pk_add_f32 v[84:85], v[84:85], v[86:87]
	v_pk_add_f32 v[88:89], v[88:89], v[90:91]
	v_pk_add_f32 v[92:93], v[92:93], v[94:95]
	v_pk_add_f32 v[64:65], v[64:65], v[68:69]
	v_pk_add_f32 v[72:73], v[72:73], v[76:77]
	v_pk_add_f32 v[80:81], v[80:81], v[84:85]
	v_pk_add_f32 v[88:89], v[88:89], v[92:93]
	v_pk_add_f32 v[64:65], v[64:65], v[72:73]
	v_pk_add_f32 v[80:81], v[80:81], v[88:89]
	v_pk_add_f32 v[64:65], v[64:65], v[80:81]
	v_add_f32_e32 v64, v64, v65
	v_fmamk_f32 v64, v64, 0x3a000000, v223
	v_cmp_gt_f32_e32 vcc, s58, v64
	v_mul_f32_e32 v65, 0x4b800000, v64
	s_nop 0
	v_cndmask_b32_e32 v64, v64, v65, vcc
	v_rsq_f32_e32 v64, v64
	s_nop 0
	v_mul_f32_e32 v65, 0x45800000, v64
	v_cndmask_b32_e32 v64, v64, v65, vcc
	v_lshl_add_u32 v66, v222, 2, v227
	ds_write_b32 v66, v64
.Lxss_done_b:
	s_or_b64 exec, exec, s[100:101]
	s_waitcnt lgkmcnt(0)
	s_barrier
	v_mad_u64_u32 v[164:165], s[52:53], v35, s9, v[42:43]
	v_mad_u32_u24 v163, v43, s9, v42
	s_waitcnt vmcnt(7)
	ds_write_b128 v162, v[2:5]
	s_waitcnt vmcnt(6)
	ds_write_b128 v162, v[6:9] offset:36864
	s_waitcnt vmcnt(5)
	ds_write_b128 v162, v[10:13] offset:9216
	s_waitcnt vmcnt(4)
	ds_write_b128 v162, v[14:17] offset:46080
	s_waitcnt vmcnt(3)
	ds_write_b128 v162, v[18:21] offset:18432
	s_waitcnt vmcnt(2)
	ds_write_b128 v162, v[22:25] offset:55296
	s_waitcnt vmcnt(1)
	ds_write_b128 v162, v[26:29] offset:27648
	s_waitcnt vmcnt(0)
	ds_write_b128 v162, v[30:33] offset:64512
	global_load_dwordx4 v[130:133], v[38:39], off offset:128
	global_load_dwordx4 v[134:137], v[40:41], off offset:128
	global_load_dwordx4 v[138:141], v[44:45], off offset:128
	global_load_dwordx4 v[142:145], v[46:47], off offset:128
	global_load_dwordx4 v[146:149], v[48:49], off offset:128
	global_load_dwordx4 v[150:153], v[50:51], off offset:128
	global_load_dwordx4 v[154:157], v[52:53], off offset:128
	global_load_dwordx4 v[158:161], v[54:55], off offset:128
	v_lshl_add_u64 v[2:3], s[0:1], 0, v[36:37]
	v_lshl_add_u64 v[2:3], v[2:3], 0, v[0:1]
	v_lshl_add_u64 v[166:167], s[14:15], 0, v[2:3]
	v_lshl_add_u64 v[2:3], s[4:5], 0, v[36:37]
	v_lshl_add_u64 v[2:3], v[2:3], 0, v[0:1]
	v_lshl_add_u64 v[168:169], s[40:41], 0, v[2:3]
	v_mov_b32_e32 v2, 0
	s_mov_b64 s[0:1], 0
	s_mov_b32 s4, 2
	v_mov_b32_e32 v3, v2
	v_mov_b32_e32 v4, v2
	v_mov_b32_e32 v5, v2
	v_mov_b32_e32 v6, v2
	v_mov_b32_e32 v7, v2
	v_mov_b32_e32 v8, v2
	v_mov_b32_e32 v9, v2
	v_mov_b32_e32 v10, v2
	v_mov_b32_e32 v11, v2
	v_mov_b32_e32 v12, v2
	v_mov_b32_e32 v13, v2
	v_mov_b32_e32 v14, v2
	v_mov_b32_e32 v15, v2
	v_mov_b32_e32 v16, v2
	v_mov_b32_e32 v17, v2
	v_mov_b32_e32 v18, v2
	v_mov_b32_e32 v19, v2
	v_mov_b32_e32 v20, v2
	v_mov_b32_e32 v21, v2
	v_mov_b32_e32 v22, v2
	v_mov_b32_e32 v23, v2
	v_mov_b32_e32 v24, v2
	v_mov_b32_e32 v25, v2
	v_mov_b32_e32 v26, v2
	v_mov_b32_e32 v27, v2
	v_mov_b32_e32 v28, v2
	v_mov_b32_e32 v29, v2
	v_mov_b32_e32 v30, v2
	v_mov_b32_e32 v31, v2
	v_mov_b32_e32 v32, v2
	v_mov_b32_e32 v33, v2
	v_mov_b32_e32 v34, v2
	v_mov_b32_e32 v35, v2
	v_mov_b32_e32 v36, v2
	v_mov_b32_e32 v37, v2
	v_mov_b32_e32 v38, v2
	v_mov_b32_e32 v39, v2
	v_mov_b32_e32 v40, v2
	v_mov_b32_e32 v41, v2
	v_mov_b32_e32 v42, v2
	v_mov_b32_e32 v43, v2
	v_mov_b32_e32 v44, v2
	v_mov_b32_e32 v45, v2
	v_mov_b32_e32 v46, v2
	v_mov_b32_e32 v47, v2
	v_mov_b32_e32 v48, v2
	v_mov_b32_e32 v49, v2
	v_mov_b32_e32 v50, v2
	v_mov_b32_e32 v51, v2
	v_mov_b32_e32 v52, v2
	v_mov_b32_e32 v53, v2
	v_mov_b32_e32 v54, v2
	v_mov_b32_e32 v55, v2
	v_mov_b32_e32 v56, v2
	v_mov_b32_e32 v57, v2
	v_mov_b32_e32 v58, v2
	v_mov_b32_e32 v59, v2
	v_mov_b32_e32 v60, v2
	v_mov_b32_e32 v61, v2
	v_mov_b32_e32 v62, v2
	v_mov_b32_e32 v63, v2
	v_mov_b32_e32 v64, v2
	v_mov_b32_e32 v65, v2
	v_mov_b32_e32 v66, v2
	v_mov_b32_e32 v67, v2
	v_mov_b32_e32 v68, v2
	v_mov_b32_e32 v69, v2
	v_mov_b32_e32 v70, v2
	v_mov_b32_e32 v71, v2
; #define MFMA32(a, b, c) __builtin_amdgcn_mfma_f32_32x32x16_bf16((a), (b), (c), 0, 0, 0)
; template <bool SWAP, bool SSQ, bool ZERO = true>
; DI void gemm_main(const u16* __restrict__ A, int lda, const u16* __restrict__ Bt, int ldb, int K, char* lds,
;                   f32x16 (&acc)[4][2], float* rs_lds) {
;     ...
;   for (int kt = 0; kt < nk; ++kt) {
;     const int st = (kt & 1) * 2 * G_TILE;
;     {
;       bf16x8 fa[2][4], fb[2][2];
; #pragma unroll
;       for (int i = 0; i < 4; ++i) fa[0][i] = *(const bf16x8*)(abase + st + i * 32 * GS);
; #pragma unroll
;       for (int i = 0; i < 2; ++i) fb[0][i] = *(const bf16x8*)(bbase + st + i * 32 * GS);
; #pragma unroll
;       for (int ks = 0; ks < 4; ++ks) {
;         if (ks + 1 < 4) {
; #pragma unroll
;           for (int i = 0; i < 4; ++i) fa[(ks + 1) & 1][i] = *(const bf16x8*)(abase + st + i * 32 * GS + (ks + 1) * 32);
; #pragma unroll
;           for (int i = 0; i < 2; ++i) fb[(ks + 1) & 1][i] = *(const bf16x8*)(bbase + st + i * 32 * GS + (ks + 1) * 32);
;         }
;         __builtin_amdgcn_sched_barrier(0);
;         __builtin_amdgcn_s_setprio(1);
; #pragma unroll
;         for (int mt = 0; mt < 4; ++mt)
; #pragma unroll
;           for (int nt = 0; nt < 2; ++nt)
;             acc[mt][nt] = SWAP ? MFMA32(fb[ks & 1][nt], fa[ks & 1][mt], acc[mt][nt]) : MFMA32(fa[ks & 1][mt], fb[ks & 1][nt], acc[mt][nt]);
;         __builtin_amdgcn_s_setprio(0);
;         __builtin_amdgcn_sched_barrier(0);
;       }
	v_mov_b32_e32 v72, v2
	v_mov_b32_e32 v73, v2
	v_mov_b32_e32 v74, v2
	v_mov_b32_e32 v75, v2
	v_mov_b32_e32 v76, v2
	v_mov_b32_e32 v77, v2
	v_mov_b32_e32 v78, v2
	v_mov_b32_e32 v79, v2
	v_mov_b32_e32 v80, v2
	v_mov_b32_e32 v81, v2
	v_mov_b32_e32 v82, v2
	v_mov_b32_e32 v83, v2
	v_mov_b32_e32 v84, v2
	v_mov_b32_e32 v85, v2
	v_mov_b32_e32 v86, v2
	v_mov_b32_e32 v87, v2
	v_mov_b32_e32 v88, v2
	v_mov_b32_e32 v89, v2
	v_mov_b32_e32 v90, v2
	v_mov_b32_e32 v91, v2
	v_mov_b32_e32 v92, v2
	v_mov_b32_e32 v93, v2
	v_mov_b32_e32 v94, v2
	v_mov_b32_e32 v95, v2
	v_mov_b32_e32 v96, v2
	v_mov_b32_e32 v97, v2
	v_mov_b32_e32 v98, v2
	v_mov_b32_e32 v99, v2
	v_mov_b32_e32 v100, v2
	v_mov_b32_e32 v101, v2
	v_mov_b32_e32 v102, v2
	v_mov_b32_e32 v103, v2
	v_mov_b32_e32 v104, v2
	v_mov_b32_e32 v105, v2
	v_mov_b32_e32 v106, v2
	v_mov_b32_e32 v107, v2
	v_mov_b32_e32 v108, v2
	v_mov_b32_e32 v109, v2
	v_mov_b32_e32 v110, v2
	v_mov_b32_e32 v111, v2
	v_mov_b32_e32 v112, v2
	v_mov_b32_e32 v113, v2
	v_mov_b32_e32 v114, v2
	v_mov_b32_e32 v115, v2
	v_mov_b32_e32 v116, v2
	v_mov_b32_e32 v117, v2
	v_mov_b32_e32 v118, v2
	v_mov_b32_e32 v119, v2
	v_mov_b32_e32 v120, v2
	v_mov_b32_e32 v121, v2
	v_mov_b32_e32 v122, v2
	v_mov_b32_e32 v123, v2
	v_mov_b32_e32 v124, v2
	v_mov_b32_e32 v125, v2
	v_mov_b32_e32 v126, v2
	v_mov_b32_e32 v127, v2
	v_mov_b32_e32 v128, v2
	v_mov_b32_e32 v129, v2
	s_add_i32 s52, s4, -2
	s_and_b32 s52, s52, 2
	s_mul_i32 s52, s52, 0x9000
	v_add_u32_e32 v0, s52, v164
	v_add_u32_e32 v165, s52, v163
	s_waitcnt lgkmcnt(0)
	s_barrier
	s_branch .LBB0_119
.LBB0_118:
	s_add_u32 s0, s0, 0x80
	s_addc_u32 s1, s1, 0
	s_add_i32 s4, s4, 2
	s_add_i32 s2, s2, 1
	s_add_i32 s52, s4, -2
	s_and_b32 s52, s52, 2
	s_mul_i32 s52, s52, 0x9000
	v_add_u32_e32 v0, s52, v164
	v_add_u32_e32 v165, s52, v163
	s_cmpk_lg_i32 s0, 0x1000
	s_waitcnt lgkmcnt(0)
	s_barrier
	s_cbranch_scc0 .LBB0_85
.LBB0_119:
	ds_read_b128 v[170:173], v0
	ds_read_b128 v[202:205], v165 offset:36864
	ds_read_b128 v[210:213], v165 offset:41472
	ds_read_b128 v[178:181], v0 offset:4608
	ds_read_b128 v[186:189], v0 offset:9216
	ds_read_b128 v[194:197], v0 offset:13824
	ds_read_b128 v[174:177], v0 offset:32
	ds_read_b128 v[206:209], v165 offset:36896
	ds_read_b128 v[214:217], v165 offset:41504
	ds_read_b128 v[182:185], v0 offset:4640
	ds_read_b128 v[190:193], v0 offset:9248
	ds_read_b128 v[198:201], v0 offset:13856
	s_setprio 1
	s_waitcnt lgkmcnt(10)
	v_mfma_f32_32x32x16_bf16 v[114:129], v[170:173], v[202:205], v[114:129]
	s_waitcnt lgkmcnt(9)
	v_mfma_f32_32x32x16_bf16 v[98:113], v[170:173], v[210:213], v[98:113]
	s_waitcnt lgkmcnt(8)
	v_mfma_f32_32x32x16_bf16 v[82:97], v[178:181], v[202:205], v[82:97]
	v_mfma_f32_32x32x16_bf16 v[66:81], v[178:181], v[210:213], v[66:81]
	s_waitcnt lgkmcnt(7)
	v_mfma_f32_32x32x16_bf16 v[50:65], v[186:189], v[202:205], v[50:65]
	v_mfma_f32_32x32x16_bf16 v[34:49], v[186:189], v[210:213], v[34:49]
	s_waitcnt lgkmcnt(6)
	v_mfma_f32_32x32x16_bf16 v[18:33], v[194:197], v[202:205], v[18:33]
	v_mfma_f32_32x32x16_bf16 v[2:17], v[194:197], v[210:213], v[2:17]
	s_setprio 0
	ds_read_b128 v[170:173], v0 offset:64
	ds_read_b128 v[202:205], v165 offset:36928
	ds_read_b128 v[210:213], v165 offset:41536
	ds_read_b128 v[178:181], v0 offset:4672
	ds_read_b128 v[186:189], v0 offset:9280
	ds_read_b128 v[194:197], v0 offset:13888
	s_setprio 1
	s_waitcnt lgkmcnt(10)
	v_mfma_f32_32x32x16_bf16 v[114:129], v[174:177], v[206:209], v[114:129]
	s_waitcnt lgkmcnt(9)
	v_mfma_f32_32x32x16_bf16 v[98:113], v[174:177], v[214:217], v[98:113]
	s_waitcnt lgkmcnt(8)
	v_mfma_f32_32x32x16_bf16 v[82:97], v[182:185], v[206:209], v[82:97]
	v_mfma_f32_32x32x16_bf16 v[66:81], v[182:185], v[214:217], v[66:81]
	s_waitcnt lgkmcnt(7)
	v_mfma_f32_32x32x16_bf16 v[50:65], v[190:193], v[206:209], v[50:65]
	v_mfma_f32_32x32x16_bf16 v[34:49], v[190:193], v[214:217], v[34:49]
	s_waitcnt lgkmcnt(6)
	v_mfma_f32_32x32x16_bf16 v[18:33], v[198:201], v[206:209], v[18:33]
	v_mfma_f32_32x32x16_bf16 v[2:17], v[198:201], v[214:217], v[2:17]
	s_setprio 0
	ds_read_b128 v[174:177], v0 offset:96
	ds_read_b128 v[206:209], v165 offset:36960
	ds_read_b128 v[214:217], v165 offset:41568
	ds_read_b128 v[182:185], v0 offset:4704
	ds_read_b128 v[190:193], v0 offset:9312
	ds_read_b128 v[198:201], v0 offset:13920
	s_cmp_gt_u32 s2, 29
	s_cbranch_scc1 .Lg119_tail
; #define MFMA32(a, b, c) __builtin_amdgcn_mfma_f32_32x32x16_bf16((a), (b), (c), 0, 0, 0)
; #define G_LOAD(KT) do { const int k0_ = (KT) << 6; _Pragma("unroll") for (int p = 0; p < 4; ++p) { \
;     ra[p] = *(const u32x4*)(ap + (size_t)(64 * p) * lda + k0_); rb[p] = *(const u32x4*)(bp + (size_t)(64 * p) * ldb + k0_); } } while (0)
; template <bool SWAP, bool SSQ, bool ZERO = true>
; DI void gemm_main(const u16* __restrict__ A, int lda, const u16* __restrict__ Bt, int ldb, int K, char* lds,
;                   f32x16 (&acc)[4][2], float* rs_lds) {
;     ...
;       for (int ks = 0; ks < 4; ++ks) {
;         if (ks + 1 < 4) {
; #pragma unroll
;           for (int i = 0; i < 4; ++i) fa[(ks + 1) & 1][i] = *(const bf16x8*)(abase + st + i * 32 * GS + (ks + 1) * 32);
; #pragma unroll
;           for (int i = 0; i < 2; ++i) fb[(ks + 1) & 1][i] = *(const bf16x8*)(bbase + st + i * 32 * GS + (ks + 1) * 32);
;         }
;         __builtin_amdgcn_sched_barrier(0);
;         __builtin_amdgcn_s_setprio(1);
; #pragma unroll
;         for (int mt = 0; mt < 4; ++mt)
; #pragma unroll
;           for (int nt = 0; nt < 2; ++nt)
;             acc[mt][nt] = SWAP ? MFMA32(fb[ks & 1][nt], fa[ks & 1][mt], acc[mt][nt]) : MFMA32(fa[ks & 1][mt], fb[ks & 1][nt], acc[mt][nt]);
;         __builtin_amdgcn_s_setprio(0);
;         __builtin_amdgcn_sched_barrier(0);
;       }
;     }
;     if (kt + 1 < nk) G_WRITE((kt + 1) & 1);
;     if (kt + 2 < nk) G_LOAD(kt + 2);
;     __syncthreads();
	s_setprio 1
	s_waitcnt lgkmcnt(10)
	v_mfma_f32_32x32x16_bf16 v[114:129], v[170:173], v[202:205], v[114:129]
	s_waitcnt lgkmcnt(9)
	v_mfma_f32_32x32x16_bf16 v[98:113], v[170:173], v[210:213], v[98:113]
	s_waitcnt lgkmcnt(8)
	v_mfma_f32_32x32x16_bf16 v[82:97], v[178:181], v[202:205], v[82:97]
	v_mfma_f32_32x32x16_bf16 v[66:81], v[178:181], v[210:213], v[66:81]
	s_and_b32 s52, s4, 2
	s_mul_i32 s52, s52, 0x9000
	v_add_u32_e32 v240, s52, v162
	v_lshl_add_u64 v[220:221], v[168:169], 0, s[0:1]
	v_lshl_add_u64 v[234:235], v[166:167], 0, s[0:1]
	s_waitcnt lgkmcnt(7)
	v_mfma_f32_32x32x16_bf16 v[50:65], v[186:189], v[202:205], v[50:65]
	s_waitcnt vmcnt(7)
	ds_write_b128 v240, v[130:133]
	global_load_dwordx4 v[130:133], v[220:221], off offset:256
	v_add_co_u32_e32 v220, vcc, 0x40000, v220
	v_mfma_f32_32x32x16_bf16 v[34:49], v[186:189], v[210:213], v[34:49]
	s_waitcnt vmcnt(7)
	ds_write_b128 v240, v[134:137] offset:36864
	v_addc_co_u32_e32 v221, vcc, 0, v221, vcc
	global_load_dwordx4 v[134:137], v[234:235], off offset:256
	v_add_co_u32_e32 v234, vcc, 0x40000, v234
	s_waitcnt lgkmcnt(8)
	v_mfma_f32_32x32x16_bf16 v[18:33], v[194:197], v[202:205], v[18:33]
	s_waitcnt vmcnt(7)
	ds_write_b128 v240, v[138:141] offset:9216
	v_addc_co_u32_e32 v235, vcc, 0, v235, vcc
	global_load_dwordx4 v[138:141], v[220:221], off offset:256
	v_add_co_u32_e32 v220, vcc, 0x40000, v220
	v_mfma_f32_32x32x16_bf16 v[2:17], v[194:197], v[210:213], v[2:17]
	s_waitcnt vmcnt(7)
	ds_write_b128 v240, v[142:145] offset:46080
	v_addc_co_u32_e32 v221, vcc, 0, v221, vcc
	global_load_dwordx4 v[142:145], v[234:235], off offset:256
	v_add_co_u32_e32 v234, vcc, 0x40000, v234
	s_waitcnt lgkmcnt(8)
	v_mfma_f32_32x32x16_bf16 v[114:129], v[174:177], v[206:209], v[114:129]
	s_waitcnt vmcnt(7)
	ds_write_b128 v240, v[146:149] offset:18432
	v_addc_co_u32_e32 v235, vcc, 0, v235, vcc
	global_load_dwordx4 v[146:149], v[220:221], off offset:256
	v_add_co_u32_e32 v220, vcc, 0x40000, v220
	s_waitcnt lgkmcnt(8)
	v_mfma_f32_32x32x16_bf16 v[98:113], v[174:177], v[214:217], v[98:113]
	s_waitcnt vmcnt(7)
	ds_write_b128 v240, v[150:153] offset:55296
	v_addc_co_u32_e32 v221, vcc, 0, v221, vcc
	global_load_dwordx4 v[150:153], v[234:235], off offset:256
	v_add_co_u32_e32 v234, vcc, 0x40000, v234
	s_waitcnt lgkmcnt(8)
	v_mfma_f32_32x32x16_bf16 v[82:97], v[182:185], v[206:209], v[82:97]
	s_waitcnt vmcnt(7)
	ds_write_b128 v240, v[154:157] offset:27648
	v_addc_co_u32_e32 v235, vcc, 0, v235, vcc
	global_load_dwordx4 v[154:157], v[220:221], off offset:256
	v_mfma_f32_32x32x16_bf16 v[66:81], v[182:185], v[214:217], v[66:81]
	s_waitcnt vmcnt(7)
	ds_write_b128 v240, v[158:161] offset:64512
	global_load_dwordx4 v[158:161], v[234:235], off offset:256
	s_waitcnt lgkmcnt(9)
	v_mfma_f32_32x32x16_bf16 v[50:65], v[190:193], v[206:209], v[50:65]
	v_mfma_f32_32x32x16_bf16 v[34:49], v[190:193], v[214:217], v[34:49]
	s_waitcnt lgkmcnt(8)
	v_mfma_f32_32x32x16_bf16 v[18:33], v[198:201], v[206:209], v[18:33]
	v_mfma_f32_32x32x16_bf16 v[2:17], v[198:201], v[214:217], v[2:17]
	s_setprio 0
	s_branch .LBB0_118
.Lg119_tail:
	s_setprio 1
	s_waitcnt lgkmcnt(10)
	v_mfma_f32_32x32x16_bf16 v[114:129], v[170:173], v[202:205], v[114:129]
	s_waitcnt lgkmcnt(9)
	v_mfma_f32_32x32x16_bf16 v[98:113], v[170:173], v[210:213], v[98:113]
	s_waitcnt lgkmcnt(8)
	v_mfma_f32_32x32x16_bf16 v[82:97], v[178:181], v[202:205], v[82:97]
	v_mfma_f32_32x32x16_bf16 v[66:81], v[178:181], v[210:213], v[66:81]
	s_waitcnt lgkmcnt(7)
	v_mfma_f32_32x32x16_bf16 v[50:65], v[186:189], v[202:205], v[50:65]
	v_mfma_f32_32x32x16_bf16 v[34:49], v[186:189], v[210:213], v[34:49]
	s_waitcnt lgkmcnt(6)
	v_mfma_f32_32x32x16_bf16 v[18:33], v[194:197], v[202:205], v[18:33]
	v_mfma_f32_32x32x16_bf16 v[2:17], v[194:197], v[210:213], v[2:17]
	s_waitcnt lgkmcnt(4)
	v_mfma_f32_32x32x16_bf16 v[114:129], v[174:177], v[206:209], v[114:129]
	s_waitcnt lgkmcnt(3)
	v_mfma_f32_32x32x16_bf16 v[98:113], v[174:177], v[214:217], v[98:113]
	s_waitcnt lgkmcnt(2)
	v_mfma_f32_32x32x16_bf16 v[82:97], v[182:185], v[206:209], v[82:97]
	v_mfma_f32_32x32x16_bf16 v[66:81], v[182:185], v[214:217], v[66:81]
	s_waitcnt lgkmcnt(1)
	v_mfma_f32_32x32x16_bf16 v[50:65], v[190:193], v[206:209], v[50:65]
	v_mfma_f32_32x32x16_bf16 v[34:49], v[190:193], v[214:217], v[34:49]
	s_waitcnt lgkmcnt(0)
	v_mfma_f32_32x32x16_bf16 v[18:33], v[198:201], v[206:209], v[18:33]
	v_mfma_f32_32x32x16_bf16 v[2:17], v[198:201], v[214:217], v[2:17]
	s_setprio 0
	s_cmpk_eq_i32 s0, 0xf80
	s_cbranch_scc1 .LBB0_121
	s_and_b32 s52, s4, 2
	s_mul_i32 s52, s52, 0x9000
	v_add_u32_e32 v0, s52, v162
	s_waitcnt vmcnt(7)
	ds_write_b128 v0, v[130:133]
	s_waitcnt vmcnt(6)
	ds_write_b128 v0, v[134:137] offset:36864
	s_waitcnt vmcnt(5)
	ds_write_b128 v0, v[138:141] offset:9216
	s_waitcnt vmcnt(4)
	ds_write_b128 v0, v[142:145] offset:46080
	s_waitcnt vmcnt(3)
	ds_write_b128 v0, v[146:149] offset:18432
	s_waitcnt vmcnt(2)
	ds_write_b128 v0, v[150:153] offset:55296
	s_waitcnt vmcnt(1)
	ds_write_b128 v0, v[154:157] offset:27648
	s_waitcnt vmcnt(0)
	ds_write_b128 v0, v[158:161] offset:64512

; DI int tid() { int t = threadIdx.x; asm volatile("" : "+v"(t)); return t; }
; #define G_LOAD(KT) do { const int k0_ = (KT) << 6; _Pragma("unroll") for (int p = 0; p < 4; ++p) { \
;     ra[p] = *(const u32x4*)(ap + (size_t)(64 * p) * lda + k0_); rb[p] = *(const u32x4*)(bp + (size_t)(64 * p) * ldb + k0_); } } while (0)
; template <bool SWAP, bool SSQ, bool ZERO = true>
; DI void gemm_main(const u16* __restrict__ A, int lda, const u16* __restrict__ Bt, int ldb, int K, char* lds,
;                   f32x16 (&acc)[4][2], float* rs_lds) {
;     ...
;   G_LOAD(0);
;   __syncthreads();
;   G_WRITE(0);
;   G_LOAD(1);
;   __syncthreads();
; DI void out_tile(const Params& p, int l, int mi, int ni, char* lds) {
;     ...
;   const float* xs = (l == 0) ? p.x : p.X;
;   const int t = tid(), lane = t & 63, w = t >> 6, wm = w >> 2, wn = w & 3, r = lane & 31, hf = lane >> 5;
; #pragma unroll
;   for (int mt = 0; mt < 4; ++mt) {
;     const float* xr = xs + (size_t)(m0 + wm * 128 + mt * 32 + r) * DM + n0 + wn * 64 + 4 * hf;
; #pragma unroll
;     for (int nt = 0; nt < 2; ++nt)
; #pragma unroll
;       for (int g = 0; g < 4; ++g) {
;         const f32x4 v = *(const f32x4*)(xr + nt * 32 + 8 * g);
;         acc[mt][nt][4 * g] = v[0]; acc[mt][nt][4 * g + 1] = v[1]; acc[mt][nt][4 * g + 2] = v[2]; acc[mt][nt][4 * g + 3] = v[3];
;       }
;   }
.LBB0_290:
	s_and_b32 s0, s63, 31
	s_ashr_i32 s84, s81, 5
	s_lshl_b32 s4, s0, 20
	s_lshl_b32 s0, s84, 8
	v_mov_b32_e32 v0, v222
	s_ashr_i32 s1, s0, 31
	v_ashrrev_i32_e32 v2, 1, v0
	s_and_b32 s85, s81, 31
	v_and_b32_e32 v2, 0xffffff80, v2
	s_lshl_b64 s[82:83], s[0:1], 2
	v_bfe_u32 v173, v0, 6, 2
	v_lshl_add_u32 v2, s85, 8, v2
	s_add_u32 s82, s52, s82
	v_bfe_u32 v171, v0, 5, 1
	v_and_or_b32 v168, v0, 31, v2
	s_addc_u32 s83, s2, s83
	v_lshlrev_b32_e32 v0, 8, v173
	v_lshl_add_u64 v[2:3], s[82:83], 0, v[0:1]
	v_lshlrev_b32_e32 v0, 4, v171
	v_ashrrev_i32_e32 v169, 31, v168
	v_lshl_add_u64 v[2:3], v[2:3], 0, v[0:1]
	v_lshlrev_b64 v[4:5], 13, v[168:169]
	v_or_b32_e32 v166, 32, v168
	v_lshl_add_u64 v[4:5], v[2:3], 0, v[4:5]
	v_ashrrev_i32_e32 v167, 31, v166
	global_load_dwordx4 v[114:117], v[4:5], off
	global_load_dwordx4 v[118:121], v[4:5], off offset:32
	global_load_dwordx4 v[122:125], v[4:5], off offset:64
	global_load_dwordx4 v[126:129], v[4:5], off offset:96
	global_load_dwordx4 v[98:101], v[4:5], off offset:128
	global_load_dwordx4 v[102:105], v[4:5], off offset:160
	global_load_dwordx4 v[106:109], v[4:5], off offset:192
	global_load_dwordx4 v[110:113], v[4:5], off offset:224
	v_lshlrev_b64 v[4:5], 13, v[166:167]
	v_or_b32_e32 v164, 64, v168
	v_lshl_add_u64 v[4:5], v[2:3], 0, v[4:5]
	v_ashrrev_i32_e32 v165, 31, v164
	global_load_dwordx4 v[82:85], v[4:5], off
	global_load_dwordx4 v[86:89], v[4:5], off offset:32
	global_load_dwordx4 v[90:93], v[4:5], off offset:64
	global_load_dwordx4 v[94:97], v[4:5], off offset:96
	global_load_dwordx4 v[66:69], v[4:5], off offset:128
	global_load_dwordx4 v[70:73], v[4:5], off offset:160
	global_load_dwordx4 v[74:77], v[4:5], off offset:192
	global_load_dwordx4 v[78:81], v[4:5], off offset:224
	v_lshlrev_b64 v[4:5], 13, v[164:165]
	v_or_b32_e32 v162, 0x60, v168
	v_lshl_add_u64 v[4:5], v[2:3], 0, v[4:5]
	v_ashrrev_i32_e32 v163, 31, v162
	global_load_dwordx4 v[50:53], v[4:5], off
	global_load_dwordx4 v[54:57], v[4:5], off offset:32
	global_load_dwordx4 v[58:61], v[4:5], off offset:64
	global_load_dwordx4 v[62:65], v[4:5], off offset:96
	global_load_dwordx4 v[34:37], v[4:5], off offset:128
	global_load_dwordx4 v[38:41], v[4:5], off offset:160
	global_load_dwordx4 v[42:45], v[4:5], off offset:192
	global_load_dwordx4 v[46:49], v[4:5], off offset:224
	v_lshlrev_b64 v[4:5], 13, v[162:163]
	v_lshl_add_u64 v[14:15], v[2:3], 0, v[4:5]
	v_mov_b32_e32 v176, v222
	global_load_dwordx4 v[18:21], v[14:15], off
	global_load_dwordx4 v[22:25], v[14:15], off offset:32
	global_load_dwordx4 v[26:29], v[14:15], off offset:64
	global_load_dwordx4 v[30:33], v[14:15], off offset:96
	global_load_dwordx4 v[2:5], v[14:15], off offset:128
	global_load_dwordx4 v[6:9], v[14:15], off offset:160
	global_load_dwordx4 v[10:13], v[14:15], off offset:192
	s_nop 0
	global_load_dwordx4 v[14:17], v[14:15], off offset:224
	s_lshl_b32 s82, s85, 20
	s_add_u32 s86, s34, s82
	v_ashrrev_i32_e32 v174, 3, v176
	v_ashrrev_i32_e32 v175, 31, v174
	s_addc_u32 s87, s35, 0
	s_lshl_b64 s[82:83], s[0:1], 12
	v_lshlrev_b64 v[180:181], 12, v[174:175]
	s_waitcnt vmcnt(34)
	v_lshlrev_b32_e32 v132, 4, v176
	s_add_u32 s88, s53, s82
	v_lshl_add_u64 v[130:131], s[86:87], 0, v[180:181]
	v_and_b32_e32 v182, 0x70, v132
	v_mov_b32_e32 v183, v1
	s_addc_u32 s89, s62, s83
	v_lshl_add_u64 v[130:131], v[130:131], 0, v[182:183]
	v_lshl_add_u64 v[132:133], s[88:89], 0, v[180:181]
	s_waitcnt vmcnt(33)
	v_add_co_u32_e32 v138, vcc, s54, v130
	v_lshl_add_u64 v[134:135], v[132:133], 0, v[182:183]
	s_nop 0
	v_addc_co_u32_e32 v139, vcc, 0, v131, vcc
	s_waitcnt vmcnt(32)
	v_add_co_u32_e32 v142, vcc, s54, v134
	global_load_dwordx4 v[184:187], v[130:131], off
	global_load_dwordx4 v[188:191], v[134:135], off
	v_addc_co_u32_e32 v143, vcc, 0, v135, vcc
	v_add_co_u32_e32 v146, vcc, s55, v130
	global_load_dwordx4 v[192:195], v[138:139], off
	s_nop 0
	v_addc_co_u32_e32 v147, vcc, 0, v131, vcc
	v_add_co_u32_e32 v150, vcc, s55, v134
	global_load_dwordx4 v[196:199], v[142:143], off
	s_nop 0
	v_addc_co_u32_e32 v151, vcc, 0, v135, vcc
	v_add_co_u32_e32 v154, vcc, s8, v130
	global_load_dwordx4 v[200:203], v[146:147], off
	s_nop 0
	v_addc_co_u32_e32 v155, vcc, 0, v131, vcc
	v_add_co_u32_e32 v158, vcc, s8, v134
	global_load_dwordx4 v[204:207], v[150:151], off
	s_nop 0
	v_addc_co_u32_e32 v159, vcc, 0, v135, vcc
	global_load_dwordx4 v[208:211], v[154:155], off
	global_load_dwordx4 v[212:215], v[158:159], off
	s_barrier
	global_load_dwordx4 v[130:133], v[130:131], off offset:128
	s_nop 0
	global_load_dwordx4 v[134:137], v[134:135], off offset:128
	s_nop 0
	global_load_dwordx4 v[138:141], v[138:139], off offset:128
	s_nop 0
	global_load_dwordx4 v[142:145], v[142:143], off offset:128
	s_nop 0
	global_load_dwordx4 v[146:149], v[146:147], off offset:128
	s_nop 0
	global_load_dwordx4 v[150:153], v[150:151], off offset:128
	s_nop 0
	global_load_dwordx4 v[154:157], v[154:155], off offset:128
	s_nop 0
	global_load_dwordx4 v[158:161], v[158:159], off offset:128
	v_and_b32_e32 v175, 31, v176
	v_lshrrev_b32_e32 v177, 1, v176
	v_and_b32_e32 v183, 0xdf, v176
	v_and_or_b32 v179, v177, s7, v175
	v_and_b32_e32 v178, 16, v177
	v_mad_u64_u32 v[174:175], s[88:89], v174, s9, v[182:183]
	v_mad_u64_u32 v[176:177], s[88:89], v179, s9, v[178:179]
	v_mad_u32_u24 v175, v183, s9, v178
	v_lshl_add_u64 v[178:179], v[180:181], 0, s[82:83]
	v_lshl_add_u64 v[180:181], s[4:5], 0, v[180:181]
	v_or_b32_e32 v178, v178, v182
	v_or_b32_e32 v180, v180, v182
	s_mov_b32 s85, 2
	v_lshlrev_b32_e32 v172, 6, v173
	v_lshlrev_b32_e32 v170, 2, v171
	s_mov_b32 s86, 0
	v_lshl_add_u64 v[178:179], s[76:77], 0, v[178:179]
	v_lshl_add_u64 v[180:181], s[34:35], 0, v[180:181]
	s_mov_b64 s[82:83], 0
	s_waitcnt vmcnt(15)
	ds_write_b128 v174, v[184:187]
	s_waitcnt vmcnt(14)
	ds_write_b128 v174, v[188:191] offset:36864
	s_waitcnt vmcnt(13)
	ds_write_b128 v174, v[192:195] offset:9216
	s_waitcnt vmcnt(12)
	ds_write_b128 v174, v[196:199] offset:46080
	s_waitcnt vmcnt(11)
	ds_write_b128 v174, v[200:203] offset:18432
	s_waitcnt vmcnt(10)
	ds_write_b128 v174, v[204:207] offset:55296
	s_waitcnt vmcnt(9)
	ds_write_b128 v174, v[208:211] offset:27648
	s_waitcnt vmcnt(8)
	ds_write_b128 v174, v[212:215] offset:64512
	s_add_i32 s4, s85, -2
	s_and_b32 s4, s4, 2
	s_mul_i32 s4, s4, 0x9000
	v_add_u32_e32 v177, s4, v176
	v_add_u32_e32 v240, s4, v175
	s_waitcnt lgkmcnt(0)
	s_barrier
	s_branch .LBB0_292
; #define MFMA32(a, b, c) __builtin_amdgcn_mfma_f32_32x32x16_bf16((a), (b), (c), 0, 0, 0)
; #define G_LOAD(KT) do { const int k0_ = (KT) << 6; _Pragma("unroll") for (int p = 0; p < 4; ++p) { \
;     ra[p] = *(const u32x4*)(ap + (size_t)(64 * p) * lda + k0_); rb[p] = *(const u32x4*)(bp + (size_t)(64 * p) * ldb + k0_); } } while (0)
; template <bool SWAP, bool SSQ, bool ZERO = true>
; DI void gemm_main(const u16* __restrict__ A, int lda, const u16* __restrict__ Bt, int ldb, int K, char* lds,
;                   f32x16 (&acc)[4][2], float* rs_lds) {
;     ...
;   for (int kt = 0; kt < nk; ++kt) {
;     const int st = (kt & 1) * 2 * G_TILE;
;     {
;       bf16x8 fa[2][4], fb[2][2];
; #pragma unroll
;       for (int i = 0; i < 4; ++i) fa[0][i] = *(const bf16x8*)(abase + st + i * 32 * GS);
; #pragma unroll
;       for (int i = 0; i < 2; ++i) fb[0][i] = *(const bf16x8*)(bbase + st + i * 32 * GS);
; #pragma unroll
;       for (int ks = 0; ks < 4; ++ks) {
;         if (ks + 1 < 4) {
; #pragma unroll
;           for (int i = 0; i < 4; ++i) fa[(ks + 1) & 1][i] = *(const bf16x8*)(abase + st + i * 32 * GS + (ks + 1) * 32);
; #pragma unroll
;           for (int i = 0; i < 2; ++i) fb[(ks + 1) & 1][i] = *(const bf16x8*)(bbase + st + i * 32 * GS + (ks + 1) * 32);
;         }
;         __builtin_amdgcn_sched_barrier(0);
;         __builtin_amdgcn_s_setprio(1);
; #pragma unroll
;         for (int mt = 0; mt < 4; ++mt)
; #pragma unroll
;           for (int nt = 0; nt < 2; ++nt)
;             acc[mt][nt] = SWAP ? MFMA32(fb[ks & 1][nt], fa[ks & 1][mt], acc[mt][nt]) : MFMA32(fa[ks & 1][mt], fb[ks & 1][nt], acc[mt][nt]);
;         __builtin_amdgcn_s_setprio(0);
;         __builtin_amdgcn_sched_barrier(0);
;       }
;     }
;     if (kt + 1 < nk) G_WRITE((kt + 1) & 1);
;     if (kt + 2 < nk) G_LOAD(kt + 2);
;     __syncthreads();
;   }
.LBB0_291:
	s_add_u32 s82, s82, 0x80
	s_addc_u32 s83, s83, 0
	s_add_i32 s85, s85, 2
	s_add_i32 s86, s86, 1
	s_add_i32 s4, s85, -2
	s_and_b32 s4, s4, 2
	s_mul_i32 s4, s4, 0x9000
	v_add_u32_e32 v177, s4, v176
	v_add_u32_e32 v240, s4, v175
	s_cmpk_lg_i32 s82, 0x1000
	s_waitcnt lgkmcnt(0)
	s_barrier
	s_cbranch_scc0 .LBB0_296
.LBB0_292:
	ds_read_b128 v[214:217], v240 offset:36864
	ds_read_b128 v[182:185], v177
	ds_read_b128 v[232:235], v240 offset:41472
	ds_read_b128 v[190:193], v177 offset:4608
	ds_read_b128 v[198:201], v177 offset:9216
	ds_read_b128 v[206:209], v177 offset:13824
	ds_read_b128 v[218:221], v240 offset:36896
	ds_read_b128 v[186:189], v177 offset:32
	ds_read_b128 v[236:239], v240 offset:41504
	ds_read_b128 v[194:197], v177 offset:4640
	ds_read_b128 v[202:205], v177 offset:9248
	ds_read_b128 v[210:213], v177 offset:13856
	s_setprio 1
	s_waitcnt lgkmcnt(10)
	v_mfma_f32_32x32x16_bf16 v[114:129], v[214:217], v[182:185], v[114:129]
	s_waitcnt lgkmcnt(9)
	v_mfma_f32_32x32x16_bf16 v[98:113], v[232:235], v[182:185], v[98:113]
	s_waitcnt lgkmcnt(8)
	v_mfma_f32_32x32x16_bf16 v[82:97], v[214:217], v[190:193], v[82:97]
	v_mfma_f32_32x32x16_bf16 v[66:81], v[232:235], v[190:193], v[66:81]
	s_waitcnt lgkmcnt(7)
	v_mfma_f32_32x32x16_bf16 v[50:65], v[214:217], v[198:201], v[50:65]
	v_mfma_f32_32x32x16_bf16 v[34:49], v[232:235], v[198:201], v[34:49]
	s_waitcnt lgkmcnt(6)
	v_mfma_f32_32x32x16_bf16 v[18:33], v[214:217], v[206:209], v[18:33]
	v_mfma_f32_32x32x16_bf16 v[2:17], v[232:235], v[206:209], v[2:17]
	s_setprio 0
	ds_read_b128 v[214:217], v240 offset:36928
	ds_read_b128 v[182:185], v177 offset:64
	ds_read_b128 v[232:235], v240 offset:41536
	ds_read_b128 v[190:193], v177 offset:4672
	ds_read_b128 v[198:201], v177 offset:9280
	ds_read_b128 v[206:209], v177 offset:13888
	s_setprio 1
	s_waitcnt lgkmcnt(10)
	v_mfma_f32_32x32x16_bf16 v[114:129], v[218:221], v[186:189], v[114:129]
	s_waitcnt lgkmcnt(9)
	v_mfma_f32_32x32x16_bf16 v[98:113], v[236:239], v[186:189], v[98:113]
	s_waitcnt lgkmcnt(8)
	v_mfma_f32_32x32x16_bf16 v[82:97], v[218:221], v[194:197], v[82:97]
	v_mfma_f32_32x32x16_bf16 v[66:81], v[236:239], v[194:197], v[66:81]
	s_waitcnt lgkmcnt(7)
	v_mfma_f32_32x32x16_bf16 v[50:65], v[218:221], v[202:205], v[50:65]
	v_mfma_f32_32x32x16_bf16 v[34:49], v[236:239], v[202:205], v[34:49]
	s_waitcnt lgkmcnt(6)
	v_mfma_f32_32x32x16_bf16 v[18:33], v[218:221], v[210:213], v[18:33]
	v_mfma_f32_32x32x16_bf16 v[2:17], v[236:239], v[210:213], v[2:17]
	s_setprio 0
	ds_read_b128 v[218:221], v240 offset:36960
	ds_read_b128 v[186:189], v177 offset:96
	ds_read_b128 v[236:239], v240 offset:41568
	ds_read_b128 v[194:197], v177 offset:4704
	ds_read_b128 v[202:205], v177 offset:9312
	ds_read_b128 v[210:213], v177 offset:13920
	s_cmp_gt_u32 s86, 29
	s_cbranch_scc1 .Lg292_tail
	s_setprio 1
	s_waitcnt lgkmcnt(10)
	v_mfma_f32_32x32x16_bf16 v[114:129], v[214:217], v[182:185], v[114:129]
	s_waitcnt lgkmcnt(9)
	v_mfma_f32_32x32x16_bf16 v[98:113], v[232:235], v[182:185], v[98:113]
	s_waitcnt lgkmcnt(8)
	v_mfma_f32_32x32x16_bf16 v[82:97], v[214:217], v[190:193], v[82:97]
	v_mfma_f32_32x32x16_bf16 v[66:81], v[232:235], v[190:193], v[66:81]
	s_and_b32 s4, s85, 2
	s_mul_i32 s4, s4, 0x9000
	v_add_u32_e32 v242, s4, v174
	v_lshl_add_u64 v[244:245], v[180:181], 0, s[82:83]
	v_lshl_add_u64 v[246:247], v[178:179], 0, s[82:83]
	s_waitcnt lgkmcnt(7)
	v_mfma_f32_32x32x16_bf16 v[50:65], v[214:217], v[198:201], v[50:65]
	s_waitcnt vmcnt(7)
	ds_write_b128 v242, v[130:133]
	global_load_dwordx4 v[130:133], v[244:245], off offset:256
	v_add_co_u32_e32 v244, vcc, 0x40000, v244
	v_mfma_f32_32x32x16_bf16 v[34:49], v[232:235], v[198:201], v[34:49]
	s_waitcnt vmcnt(7)
	ds_write_b128 v242, v[134:137] offset:36864
	v_addc_co_u32_e32 v245, vcc, 0, v245, vcc
	global_load_dwordx4 v[134:137], v[246:247], off offset:256
	v_add_co_u32_e32 v246, vcc, 0x40000, v246
	s_waitcnt lgkmcnt(8)
	v_mfma_f32_32x32x16_bf16 v[18:33], v[214:217], v[206:209], v[18:33]
	s_waitcnt vmcnt(7)
	ds_write_b128 v242, v[138:141] offset:9216
	v_addc_co_u32_e32 v247, vcc, 0, v247, vcc
	global_load_dwordx4 v[138:141], v[244:245], off offset:256
	v_add_co_u32_e32 v244, vcc, 0x40000, v244
	v_mfma_f32_32x32x16_bf16 v[2:17], v[232:235], v[206:209], v[2:17]
	s_waitcnt vmcnt(7)
	ds_write_b128 v242, v[142:145] offset:46080
	v_addc_co_u32_e32 v245, vcc, 0, v245, vcc
	global_load_dwordx4 v[142:145], v[246:247], off offset:256
	v_add_co_u32_e32 v246, vcc, 0x40000, v246
	s_waitcnt lgkmcnt(8)
	v_mfma_f32_32x32x16_bf16 v[114:129], v[218:221], v[186:189], v[114:129]
	s_waitcnt vmcnt(7)
	ds_write_b128 v242, v[146:149] offset:18432
	v_addc_co_u32_e32 v247, vcc, 0, v247, vcc
	global_load_dwordx4 v[146:149], v[244:245], off offset:256
	v_add_co_u32_e32 v244, vcc, 0x40000, v244
	s_waitcnt lgkmcnt(8)
	v_mfma_f32_32x32x16_bf16 v[98:113], v[236:239], v[186:189], v[98:113]
	s_waitcnt vmcnt(7)
	ds_write_b128 v242, v[150:153] offset:55296
	v_addc_co_u32_e32 v245, vcc, 0, v245, vcc
	global_load_dwordx4 v[150:153], v[246:247], off offset:256
	v_add_co_u32_e32 v246, vcc, 0x40000, v246
	s_waitcnt lgkmcnt(8)
	v_mfma_f32_32x32x16_bf16 v[82:97], v[218:221], v[194:197], v[82:97]
	s_waitcnt vmcnt(7)
	ds_write_b128 v242, v[154:157] offset:27648
	v_addc_co_u32_e32 v247, vcc, 0, v247, vcc
	global_load_dwordx4 v[154:157], v[244:245], off offset:256
	v_mfma_f32_32x32x16_bf16 v[66:81], v[236:239], v[194:197], v[66:81]
	s_waitcnt vmcnt(7)
	ds_write_b128 v242, v[158:161] offset:64512
	global_load_dwordx4 v[158:161], v[246:247], off offset:256
	s_waitcnt lgkmcnt(9)
	v_mfma_f32_32x32x16_bf16 v[50:65], v[218:221], v[202:205], v[50:65]
	v_mfma_f32_32x32x16_bf16 v[34:49], v[236:239], v[202:205], v[34:49]
	s_waitcnt lgkmcnt(8)
	v_mfma_f32_32x32x16_bf16 v[18:33], v[218:221], v[210:213], v[18:33]
	v_mfma_f32_32x32x16_bf16 v[2:17], v[236:239], v[210:213], v[2:17]
	s_setprio 0
	s_branch .LBB0_291
; #define MFMA32(a, b, c) __builtin_amdgcn_mfma_f32_32x32x16_bf16((a), (b), (c), 0, 0, 0)
; #define G_LOAD(KT) do { const int k0_ = (KT) << 6; _Pragma("unroll") for (int p = 0; p < 4; ++p) { \
;     ra[p] = *(const u32x4*)(ap + (size_t)(64 * p) * lda + k0_); rb[p] = *(const u32x4*)(bp + (size_t)(64 * p) * ldb + k0_); } } while (0)
; template <bool SWAP, bool SSQ, bool ZERO = true>
; DI void gemm_main(const u16* __restrict__ A, int lda, const u16* __restrict__ Bt, int ldb, int K, char* lds,
;                   f32x16 (&acc)[4][2], float* rs_lds) {
;     ...
;       for (int ks = 0; ks < 4; ++ks) {
;         if (ks + 1 < 4) {
; #pragma unroll
;           for (int i = 0; i < 4; ++i) fa[(ks + 1) & 1][i] = *(const bf16x8*)(abase + st + i * 32 * GS + (ks + 1) * 32);
; #pragma unroll
;           for (int i = 0; i < 2; ++i) fb[(ks + 1) & 1][i] = *(const bf16x8*)(bbase + st + i * 32 * GS + (ks + 1) * 32);
;         }
;         __builtin_amdgcn_sched_barrier(0);
;         __builtin_amdgcn_s_setprio(1);
; #pragma unroll
;         for (int mt = 0; mt < 4; ++mt)
; #pragma unroll
;           for (int nt = 0; nt < 2; ++nt)
;             acc[mt][nt] = SWAP ? MFMA32(fb[ks & 1][nt], fa[ks & 1][mt], acc[mt][nt]) : MFMA32(fa[ks & 1][mt], fb[ks & 1][nt], acc[mt][nt]);
;         __builtin_amdgcn_s_setprio(0);
;         __builtin_amdgcn_sched_barrier(0);
;       }
;     }
;     if (kt + 1 < nk) G_WRITE((kt + 1) & 1);
;     if (kt + 2 < nk) G_LOAD(kt + 2);
;     __syncthreads();
.Lg292_tail:
	s_setprio 1
	s_waitcnt lgkmcnt(10)
	v_mfma_f32_32x32x16_bf16 v[114:129], v[214:217], v[182:185], v[114:129]
	s_waitcnt lgkmcnt(9)
	v_mfma_f32_32x32x16_bf16 v[98:113], v[232:235], v[182:185], v[98:113]
	s_waitcnt lgkmcnt(8)
	v_mfma_f32_32x32x16_bf16 v[82:97], v[214:217], v[190:193], v[82:97]
	v_mfma_f32_32x32x16_bf16 v[66:81], v[232:235], v[190:193], v[66:81]
	s_waitcnt lgkmcnt(7)
	v_mfma_f32_32x32x16_bf16 v[50:65], v[214:217], v[198:201], v[50:65]
	v_mfma_f32_32x32x16_bf16 v[34:49], v[232:235], v[198:201], v[34:49]
	s_waitcnt lgkmcnt(6)
	v_mfma_f32_32x32x16_bf16 v[18:33], v[214:217], v[206:209], v[18:33]
	v_mfma_f32_32x32x16_bf16 v[2:17], v[232:235], v[206:209], v[2:17]
	s_waitcnt lgkmcnt(4)
	v_mfma_f32_32x32x16_bf16 v[114:129], v[218:221], v[186:189], v[114:129]
	s_waitcnt lgkmcnt(3)
	v_mfma_f32_32x32x16_bf16 v[98:113], v[236:239], v[186:189], v[98:113]
	s_waitcnt lgkmcnt(2)
	v_mfma_f32_32x32x16_bf16 v[82:97], v[218:221], v[194:197], v[82:97]
	v_mfma_f32_32x32x16_bf16 v[66:81], v[236:239], v[194:197], v[66:81]
	s_waitcnt lgkmcnt(1)
	v_mfma_f32_32x32x16_bf16 v[50:65], v[218:221], v[202:205], v[50:65]
	v_mfma_f32_32x32x16_bf16 v[34:49], v[236:239], v[202:205], v[34:49]
	s_waitcnt lgkmcnt(0)
	v_mfma_f32_32x32x16_bf16 v[18:33], v[218:221], v[210:213], v[18:33]
	v_mfma_f32_32x32x16_bf16 v[2:17], v[236:239], v[210:213], v[2:17]
	s_setprio 0
	s_cmpk_eq_i32 s82, 0xf80
	s_cbranch_scc1 .LBB0_294
	s_and_b32 s4, s85, 2
	s_mul_i32 s4, s4, 0x9000
	v_add_u32_e32 v177, s4, v174
	s_waitcnt vmcnt(7)
	ds_write_b128 v177, v[130:133]
	s_waitcnt vmcnt(6)
	ds_write_b128 v177, v[134:137] offset:36864
	s_waitcnt vmcnt(5)
	ds_write_b128 v177, v[138:141] offset:9216
	s_waitcnt vmcnt(4)
	ds_write_b128 v177, v[142:145] offset:46080
	s_waitcnt vmcnt(3)
	ds_write_b128 v177, v[146:149] offset:18432
	s_waitcnt vmcnt(2)
	ds_write_b128 v177, v[150:153] offset:55296
	s_waitcnt vmcnt(1)
	ds_write_b128 v177, v[154:157] offset:27648
	s_waitcnt vmcnt(0)
	ds_write_b128 v177, v[158:161] offset:64512
